# grid barrier: two staggered polls of the top-level count in flight per waiting block (v58 + poll overlap)
# speedup vs baseline: 1.0035x; 1.0035x over previous
; DEV unsigned xb_ld(unsigned* p)              { return __hip_atomic_load(p, __ATOMIC_RELAXED, __HIP_MEMORY_SCOPE_AGENT); }
; DEV unsigned xb_add(unsigned* p, unsigned v) { return __hip_atomic_fetch_add(p, v, __ATOMIC_RELAXED, __HIP_MEMORY_SCOPE_AGENT); }
; #define XB_SPIN(cond, bar) do { unsigned _sp = 0; while (cond) { __builtin_amdgcn_s_sleep(1); \
;     if ((++_sp & 255u) == 0u) { if (xb_ld(&(bar)[XB_TMO])) break; if (_sp > XB_SPIN_CAP) { atomicAdd(&(bar)[XB_TMO], 1u); break; } } } } while (0)
; DEV void xcd_barrier(const XcdBarrier& b) {
;     ...
;       const unsigned og = xb_add(&bar[XB_TOP], 1u);
;       const unsigned tg = og / nx;
;       if (og + 1u == (tg + 1u) * nx) xb_add(&bar[XB_TOPGEN], 1u);
;       else XB_SPIN(xb_ld(&bar[XB_TOPGEN]) == tg, bar);
.Lbar_poll2:
	s_sleep 6
	global_load_dword v6, v169, s[8:9] sc1
	s_add_i32 s12, s12, 1
	s_waitcnt vmcnt(1)
	v_cmp_ge_u32_e32 vcc, v5, v1
	s_cbranch_vccnz .Lbar_done
	s_sleep 6
	global_load_dword v5, v169, s[8:9] sc1
	s_waitcnt vmcnt(1)
	v_cmp_ge_u32_e32 vcc, v6, v1
	s_cbranch_vccnz .Lbar_done
	s_cmp_lt_u32 s12, 0x100000
	s_cbranch_scc1 .Lbar_poll2
